# S5 pass-B gelu with packed f32 ops (pk probe of instruction-slot hypothesis)
# baseline (speedup 1.0000x reference)
; #define LAS __attribute__((address_space(3)))
; __device__ __forceinline__ unsigned cvt_pk_bf16(float lo, float hi) { unsigned r; asm volatile("v_cvt_pk_bf16_f32 %0, %1, %2" : "=v"(r) : "v"(lo), "v"(hi)); return r; }
; __device__ __forceinline__ float sigmoidf_(float x) { return __builtin_amdgcn_rcpf(1.0f + __expf(-x)); }
; #define LDS_WAIT() asm volatile("s_waitcnt lgkmcnt(0)" ::: "memory")
; template <bool PASSB>
; __device__ __forceinline__ void s5_phase(LAS unsigned char* lds, const Params& p) {
;     ...
;             f32x4 br4[4], bi4[4];
; #pragma unroll
;             for (int q = 0; q < 4; ++q) { br4[q] = *(const LAS f32x4*)(BuL + lane * 20 + q * 4); bi4[q] = *(const LAS f32x4*)(BuL + (64 + lane) * 20 + q * 4); }
; #pragma unroll
;             for (int t = 0; t < 16; ++t) {
;                 const float bur = br4[t >> 2][t & 3], bui = bi4[t >> 2][t & 3];
;                 const float nr = are * hr - aim * hi + bur, ni = are * hi + aim * hr + bui; hr = nr; hi = ni;
;                 if (PASSB) *(LAS unsigned*)(HbL + t * 272 + lane * 4) = cvt_pk_bf16(hr, hi);
;             }
;             if (PASSB) {
;                 LDS_WAIT();
;                 f32x4 y = __builtin_amdgcn_mfma_f32_16x16x32_bf16(au, dfm, (f32x4){0.f, 0.f, 0.f, 0.f}, 0, 0, 0);
; #pragma unroll
;                 for (int ks = 0; ks < 4; ++ks) {
;                     const bf16x8 a = *(const LAS bf16x8*)(HbL + fr * 272 + (ks * 32 + fq * 8) * 2);
;                     y = __builtin_amdgcn_mfma_f32_16x16x32_bf16(a, cfm[ks], y, 0, 0, 0);
;                 }
; #pragma unroll
;                 for (int j = 0; j < 4; ++j) {
;                     const float v = y[j];
;                     const float ge = v * sigmoidf_(1.5957691216057308f * (v + 0.044715f * v * v * v));
;                     YG[(r0 + fq * 4 + j) * 1024 + g * 16 + fr] = (bf16_t)(cvt_pk_bf16(ge, ge) & 0xffffu);
;                 }
;             }
.LBB0_1093:
	s_or_b64 exec, exec, s[24:25]
	v_mfma_f32_16x16x32_bf16 v[112:115], v[68:71], v[8:11], 0
	v_mfma_f32_16x16x32_bf16 v[116:119], v[68:71], v[4:7], 0
	s_nop 6
	ds_write_b128 v107, v[112:115]
	s_add_i32 s23, s23, 1
	v_mfma_f32_16x16x32_bf16 v[120:123], v[68:71], v[16:19], 0
	v_lshl_add_u64 v[98:99], v[98:99], 0, s[64:65]
	s_cmp_eq_u32 s23, 32
	v_mfma_f32_16x16x32_bf16 v[124:127], v[68:71], v[12:15], 0
	ds_write_b128 v107, v[116:119] offset:1280
	s_nop 3
	ds_write_b128 v107, v[120:123] offset:2560
	s_nop 1
	ds_write_b128 v107, v[124:127] offset:3840
	v_mfma_f32_16x16x32_bf16 v[128:131], v[68:71], v[20:23], 0
	v_mfma_f32_16x16x32_bf16 v[112:115], v[68:71], v[24:27], 0
	v_mfma_f32_16x16x32_bf16 v[116:119], v[68:71], v[28:31], 0
	s_nop 5
	ds_write_b128 v107, v[128:131] offset:5120
	ds_write_b128 v107, v[112:115] offset:6400
	ds_write_b128 v107, v[116:119] offset:7680
	v_mfma_f32_16x16x32_bf16 v[112:115], v[68:71], v[32:35], 0
	v_mfma_f32_16x16x32_bf16 v[68:71], v[68:71], v[52:55], 0
	s_nop 6
	ds_write_b128 v107, v[112:115] offset:8960
	s_waitcnt lgkmcnt(0)
	ds_read_b128 v[112:115], v108
	ds_read_b128 v[116:119], v108 offset:16
	ds_read_b128 v[120:123], v108 offset:32
	ds_read_b128 v[124:127], v108 offset:48
	ds_read_b128 v[128:131], v108 offset:5120
	ds_read_b128 v[132:135], v108 offset:5136
	ds_read_b128 v[136:139], v108 offset:5152
	ds_read_b128 v[140:143], v108 offset:5168
	s_waitcnt lgkmcnt(3)
	v_fmac_f32_e32 v112, v88, v94
	v_fmac_f32_e32 v128, v88, v95
	v_fma_f32 v112, -v92, v95, v112
	v_fmac_f32_e32 v128, v92, v94
	v_cvt_pk_bf16_f32 v1, v112, v128
	ds_write_b32 v109, v1 offset:10240
	v_fmac_f32_e32 v113, v88, v112
	v_fmac_f32_e32 v129, v88, v128
	v_fma_f32 v113, -v92, v128, v113
	v_fmac_f32_e32 v129, v92, v112
	v_cvt_pk_bf16_f32 v152, v113, v129
	ds_write_b32 v109, v152 offset:10512
	v_fmac_f32_e32 v114, v88, v113
	v_fmac_f32_e32 v130, v88, v129
	v_fma_f32 v114, -v92, v129, v114
	v_fmac_f32_e32 v130, v92, v113
	v_cvt_pk_bf16_f32 v1, v114, v130
	ds_write_b32 v109, v1 offset:10784
	v_fmac_f32_e32 v115, v88, v114
	v_fmac_f32_e32 v131, v88, v130
	v_fma_f32 v115, -v92, v130, v115
	v_fmac_f32_e32 v131, v92, v114
	v_cvt_pk_bf16_f32 v152, v115, v131
	ds_write_b32 v109, v152 offset:11056
	s_waitcnt lgkmcnt(6)
	v_fmac_f32_e32 v116, v88, v115
	v_fmac_f32_e32 v132, v88, v131
	v_fma_f32 v116, -v92, v131, v116
	v_fmac_f32_e32 v132, v92, v115
	v_cvt_pk_bf16_f32 v1, v116, v132
	ds_write_b32 v109, v1 offset:11328
	v_fmac_f32_e32 v117, v88, v116
	v_fmac_f32_e32 v133, v88, v132
	v_fma_f32 v117, -v92, v132, v117
	v_fmac_f32_e32 v133, v92, v116
	v_cvt_pk_bf16_f32 v152, v117, v133
	ds_write_b32 v109, v152 offset:11600
	v_fmac_f32_e32 v118, v88, v117
	v_fmac_f32_e32 v134, v88, v133
	v_fma_f32 v118, -v92, v133, v118
	v_fmac_f32_e32 v134, v92, v117
	v_cvt_pk_bf16_f32 v1, v118, v134
	ds_write_b32 v109, v1 offset:11872
	v_fmac_f32_e32 v119, v88, v118
	v_fmac_f32_e32 v135, v88, v134
	v_fma_f32 v119, -v92, v134, v119
	v_fmac_f32_e32 v135, v92, v118
	v_cvt_pk_bf16_f32 v152, v119, v135
	ds_write_b32 v109, v152 offset:12144
	s_waitcnt lgkmcnt(9)
	v_fmac_f32_e32 v120, v88, v119
	v_fmac_f32_e32 v136, v88, v135
	v_fma_f32 v120, -v92, v135, v120
	v_fmac_f32_e32 v136, v92, v119
	v_cvt_pk_bf16_f32 v1, v120, v136
	ds_write_b32 v109, v1 offset:12416
	v_fmac_f32_e32 v121, v88, v120
	v_fmac_f32_e32 v137, v88, v136
	v_fma_f32 v121, -v92, v136, v121
	v_fmac_f32_e32 v137, v92, v120
	v_cvt_pk_bf16_f32 v152, v121, v137
	ds_write_b32 v109, v152 offset:12688
	v_fmac_f32_e32 v122, v88, v121
	v_fmac_f32_e32 v138, v88, v137
	v_fma_f32 v122, -v92, v137, v122
	v_fmac_f32_e32 v138, v92, v121
	v_cvt_pk_bf16_f32 v1, v122, v138
	ds_write_b32 v109, v1 offset:12960
	v_fmac_f32_e32 v123, v88, v122
	v_fmac_f32_e32 v139, v88, v138
	v_fma_f32 v123, -v92, v138, v123
	v_fmac_f32_e32 v139, v92, v122
	v_cvt_pk_bf16_f32 v152, v123, v139
	ds_write_b32 v109, v152 offset:13232
	s_waitcnt lgkmcnt(12)
	v_fmac_f32_e32 v124, v88, v123
	v_fmac_f32_e32 v140, v88, v139
	v_fma_f32 v124, -v92, v139, v124
	v_fmac_f32_e32 v140, v92, v123
	v_cvt_pk_bf16_f32 v1, v124, v140
	ds_write_b32 v109, v1 offset:13504
	v_fmac_f32_e32 v125, v88, v124
	v_fmac_f32_e32 v141, v88, v140
	v_fma_f32 v125, -v92, v140, v125
	v_fmac_f32_e32 v141, v92, v124
	v_cvt_pk_bf16_f32 v152, v125, v141
	ds_write_b32 v109, v152 offset:13776
	v_fmac_f32_e32 v126, v88, v125
	v_fmac_f32_e32 v142, v88, v141
	v_fma_f32 v126, -v92, v141, v126
	v_fmac_f32_e32 v142, v92, v125
	v_cvt_pk_bf16_f32 v1, v126, v142
	ds_write_b32 v109, v1 offset:14048
	v_fmac_f32_e32 v127, v88, v126
	v_fmac_f32_e32 v143, v88, v142
	v_fma_f32 v127, -v92, v142, v127
	v_fmac_f32_e32 v143, v92, v126
	v_cvt_pk_bf16_f32 v152, v127, v143
	ds_write_b32 v109, v152 offset:14320
	v_mov_b32_e32 v94, v127
	v_mov_b32_e32 v95, v143
	s_waitcnt lgkmcnt(0)
	ds_read_b128 v[112:115], v110 offset:10240
	ds_read_b128 v[116:119], v110 offset:10304
	s_waitcnt lgkmcnt(1)
	v_mfma_f32_16x16x32_bf16 v[68:71], v[112:115], v[36:39], v[68:71]
	ds_read_b128 v[112:115], v110 offset:10368
	s_waitcnt lgkmcnt(1)
	v_mfma_f32_16x16x32_bf16 v[68:71], v[116:119], v[40:43], v[68:71]
	ds_read_b128 v[116:119], v110 offset:10432
	s_waitcnt lgkmcnt(1)
	v_mfma_f32_16x16x32_bf16 v[68:71], v[112:115], v[44:47], v[68:71]
	v_or_b32_e32 v145, v97, v101
	v_or_b32_e32 v144, v96, v100
	v_lshlrev_b64 v[144:145], 11, v[144:145]
	s_mov_b64 s[80:81], 0x1000
	s_waitcnt lgkmcnt(0)
	v_mfma_f32_16x16x32_bf16 v[68:71], v[116:119], v[48:51], v[68:71]
	v_lshl_add_u64 v[144:145], v[2:3], 0, v[144:145]
	v_lshl_add_u64 v[146:147], v[144:145], 0, s[80:81]
	s_nop 5
	s_mov_b32 s82, 0x3d372713
	s_mov_b32 s83, 0x3d372713
	s_mov_b32 s84, 0xc0135761
	s_mov_b32 s85, 0xc0135761
	v_pk_mul_f32 v[148:149], v[68:69], s[82:83]
	v_pk_mul_f32 v[150:151], v[70:71], s[82:83]
	v_pk_mul_f32 v[148:149], v[68:69], v[148:149]
	v_pk_mul_f32 v[150:151], v[70:71], v[150:151]
	v_pk_fma_f32 v[148:149], v[68:69], v[148:149], v[68:69]
	v_pk_fma_f32 v[150:151], v[70:71], v[150:151], v[70:71]
	v_pk_mul_f32 v[148:149], v[148:149], s[84:85]
	v_pk_mul_f32 v[150:151], v[150:151], s[84:85]
	v_exp_f32_e32 v148, v148
	v_exp_f32_e32 v149, v149
	v_exp_f32_e32 v150, v150
	v_exp_f32_e32 v151, v151
	v_pk_add_f32 v[148:149], v[148:149], 1.0 op_sel_hi:[1,0]
	v_pk_add_f32 v[150:151], v[150:151], 1.0 op_sel_hi:[1,0]
	v_rcp_f32_e32 v148, v148
	v_rcp_f32_e32 v149, v149
	v_rcp_f32_e32 v150, v150
	v_rcp_f32_e32 v151, v151
	v_pk_mul_f32 v[148:149], v[68:69], v[148:149]
	v_pk_mul_f32 v[150:151], v[70:71], v[150:151]
	v_cvt_pk_bf16_f32 v148, v148, v148
	v_cvt_pk_bf16_f32 v149, v149, v149
	v_cvt_pk_bf16_f32 v150, v150, v150
	v_cvt_pk_bf16_f32 v151, v151, v151
	global_store_short v[144:145], v148, off
	global_store_short v[144:145], v149, off offset:2048
	global_store_short v[146:147], v150, off
	global_store_short v[146:147], v151, off offset:2048
	s_waitcnt lgkmcnt(0)
	v_mov_b64_e32 v[70:71], v[66:67]
	v_lshl_add_u64 v[100:101], v[100:101], 0, 16
	v_mov_b64_e32 v[68:69], v[64:65]
	s_cbranch_scc1 .LBB0_1061
